# v7 re-measure for same-session comparison with v8
# speedup vs baseline: 1.0254x; 1.0031x over previous
; #define LAS __attribute__((address_space(3)))
; DI unsigned pk2(float lo, float hi) { f32x2 v = {lo, hi}; return __builtin_bit_cast(unsigned, __builtin_convertvector(v, bf16x2v)); }
; DI void ssd_chain(const Params& p, int b, int h, bool sample, ldsp lds, int tid_) {
;   int tid = tid_; asm volatile("" : "+v"(tid));
;   const int wid = __builtin_amdgcn_readfirstlane(tid >> 6), lane = tid & 63, fr = lane & 15, fq = lane >> 4;
;   const bf16_t* proj = (const bf16_t*)(p.ws + B_PROJ);
;   const bf16_t* xact = (const bf16_t*)(p.ws + B_XACT);
;   const float* dtg = (const float*)(p.ws + B_DT); const float* lcg = (const float*)(p.ws + B_LC);
;   bf16_t* oraw = (bf16_t*)(p.ws + B_GOUT);
;   const int nchunks = sample ? 1 : 32, ntok = sample ? 4 : 64, rowbase = sample ? TP + b * 4 : b * 2048, g = h >> 2;
;   ldsp MM = lds, XW = lds + 9216, SB = lds + 18432;
;   const float Dh = p.in[18][h];
;   f32x4 Sacc[4];
;   float* sout = p.out + (sample ? O_SSMS : O_SSMP) + (size_t)(b * 8 + h) * 8192;
; #pragma unroll
;   for (int pt = 0; pt < 4; ++pt) {
;     if (sample) Sacc[pt] = *(const f32x4*)(p.in[4] + (size_t)(b * 8 + h) * 8192 + (pt * 16 + fr) * 128 + wid * 16 + 4 * fq);
;     else Sacc[pt] = (f32x4){0.f, 0.f, 0.f, 0.f};
;     u32x2 w; w.x = pk2(Sacc[pt][0], Sacc[pt][1]); w.y = pk2(Sacc[pt][2], Sacc[pt][3]);
;     *(LAS u32x2*)(SB + (pt * 16 + fr) * 272 + (wid * 16 + 4 * fq) * 2) = w;
;   }
;   u32x4 rxA = Z4, rzA = Z4, rb0A = Z4, rb1A = Z4, rc0A = Z4, rc1A = Z4; float rdtA = 0.f, rlcA = 0.f;
;   u32x4 rxB = Z4, rzB = Z4, rb0B = Z4, rb1B = Z4, rc0B = Z4, rc1B = Z4; float rdtB = 0.f, rlcB = 0.f;
;   const int tq_ = tid >> 3, pq_ = tid & 7;
.LBB0_667:
	s_cmp_gt_i32 s78, 31
	s_mov_b64 s[4:5], -1
	s_cbranch_scc0 .LBB0_788
	s_and_b32 s79, s78, 7
	s_lshl_b32 s12, s79, 2
	v_readlane_b32 s4, v248, 20
	v_mov_b32_e32 v101, v212
	v_lshrrev_b32_e32 v180, 6, v101
	v_and_b32_e32 v180, 1, v180
	v_mul_u32_u24_e32 v180, 0x180, v180
	v_xor_b32_e32 v101, v101, v180
	v_mov_b32_e32 v1, s12
	v_readlane_b32 s5, v248, 21
	s_sub_i32 s3, s78, 32
	s_lshr_b32 s61, s3, 3
	v_readfirstlane_b32 s3, v101
	s_ashr_i32 s60, s3, 6
	s_nop 0
	global_load_dword v92, v1, s[4:5]
	v_and_b32_e32 v99, 15, v101
	v_bfe_u32 v59, v101, 4, 2
	s_lshl_b32 s34, s60, 5
	v_lshlrev_b32_e32 v58, 3, v59
	s_add_i32 s35, s34, 16
	v_mul_u32_u24_e32 v114, 0x110, v99
	s_mov_b32 s53, s52
	v_add3_u32 v1, s35, v58, v114
	v_mov_b64_e32 v[2:3], s[52:53]
	ds_write_b64 v1, v[2:3] offset:18432
	ds_write_b64 v1, v[2:3] offset:22784
	ds_write_b64 v1, v[2:3] offset:27136
	ds_write_b64 v1, v[2:3] offset:31488
	s_lshl_b32 s16, s61, 11
	v_ashrrev_i32_e32 v115, 3, v101
	v_and_b32_e32 v1, 7, v101
	v_cmp_gt_i32_e64 s[4:5], 64, v115
	v_mov_b32_e32 v2, 0
	v_add_u32_e32 v4, s16, v115
	v_lshlrev_b32_e32 v94, 4, v1
	v_mov_b32_e32 v6, 0
	v_mov_b32_e32 v7, 0
	v_mov_b32_e32 v8, 0
	v_mov_b32_e32 v9, 0
	s_and_saveexec_b64 s[6:7], s[4:5]
	s_cbranch_execz .LBB0_670
	v_ashrrev_i32_e32 v5, 31, v4
	v_lshlrev_b64 v[6:7], 11, v[4:5]
	v_lshl_add_u64 v[6:7], s[62:63], 0, v[6:7]
	s_lshl_b32 s8, s79, 7
	s_mov_b32 s9, s52
	v_lshl_add_u64 v[6:7], v[6:7], 0, s[8:9]
	v_mov_b32_e32 v95, v0
	v_lshl_add_u64 v[6:7], v[6:7], 0, v[94:95]
	global_load_dwordx4 v[6:9], v[6:7], off
